# static s_setprio 1 for waves 4-7 (the younger half on each SIMD) during the attention phase, reset at conv entry
# speedup vs baseline: 1.0036x; 1.0036x over previous
; #define LAS __attribute__((address_space(3)))
; #define PH(n) if (ONLY < 0 || ONLY == (n))
; #define KARG(i) ({ unsigned long long p_; asm volatile("s_load_dwordx2 %0, %1, %2\n\ts_waitcnt lgkmcnt(0)" : "=s"(p_) : "s"((unsigned long long)__builtin_amdgcn_kernarg_segment_ptr()), "n"((i) * 8)); p_; })
; #define IN(i) ((const float*)KARG(i))
; #define WSB(off) ((bf16*)((unsigned char*)KARG(20) + (off)))
; #define WSF(off) ((float*)((unsigned char*)KARG(20) + (off)))
; __global__ void __launch_bounds__(NWAVES * 64, 2) mk_fwd(Args args) {
;     ...
;     PH(2) { PHASE_VARS
;         const float* LOGF = WSF(WS_LOGF); bf16* Z = WSB(WS_Z); bf16* CAT = WSB(WS_CAT);
;         const float* conv_w = IN(5); const float* conv_b = IN(6); const float* ln_g = IN(7); const float* ln_b = IN(8);
;         const int NV = G;
;         for (int repa = 0; repa < REPA; ++repa)
;         for (int v0 = vcu; v0 < 256; v0 += NV) {
;             const int bh = v0 >> 1, b = bh >> 3, h = bh & 7, sel = v0 & 1;
;             {
;                 LAS v4u* kxt = (LAS v4u*)(lds + attn_body::LDS_KX); const v4u* src = (const v4u*)((const unsigned char*)KARG(20) + WS_KXG) + (size_t)bh * SEQ;
; #pragma unroll
;                 for (int j = 0; j < 4; ++j) kxt[tid + 512 * j] = src[tid + 512 * j];
;                 if (tid == 0) { unsigned zz = 0u; asm volatile("" : "+v"(zz)); kxt[SEQ] = (v4u){zz, zz, zz, zz}; }
;                 __syncthreads();
;             }
;             const attn_body::bf16* Zb = (const attn_body::bf16*)Z;
;     ...
;             attn_body::bf16x8 qn0 = {}, qn1 = {}, qn2 = {}, qn3 = {};
; #pragma unroll 1
;             for (int i = 0; i < 4; ++i) {
;     ...
;                 const int qb = QB_OF(i), qbn = (i < 3) ? QB_OF(i + 1) : -1;
;                 attn_body::attn_unit<96>(b, h, qb, Zb + 1024, Zb + 1536, Zb + 2048, (attn_body::bf16*)CAT + 512, (char*)lds_raw, i == 0, qbn, qn0, qn1, qn2, qn3);
.LBB0_235:
	v_readfirstlane_b32 s98, v220
	s_bitcmp1_b32 s98, 8
	s_cbranch_scc0 .Lattn_noprio
	s_setprio 1
